# v7: attention tile loads (K,V and rope-K) issued together before the LDS staging writes in the MLA, window and selected loops; plus batched epilogue loads; W1 split + L2 prefetch
# speedup vs baseline: 1.0371x; 1.0004x over previous
; DI void load_tile_k(int tid, const bf16_t* __restrict__ g, int ld, char* dst) { u32x4 r[4]; ldg_tile(tid, g, ld, r); sts_tile_k(tid, r, dst); }
; DI void load_tile_v(int tid, const bf16_t* __restrict__ g, int ld, char* dst) { u32x4 r[4]; ldg_tile(tid, g, ld, r); sts_tile_v(tid, r, dst); }
; DI void ldg_tile(int tid, const bf16_t* __restrict__ g, int ld, u32x4 (&r)[4]) {
; #pragma unroll
;   for (int i = 0; i < 4; ++i) { const int idx = tid + 256 * i, row = idx >> 4, ch = idx & 15; r[i] = *(const u32x4*)(g + (size_t)row * ld + ch * 8); }
; }
; DI void sts_tile_k(int tid, const u32x4 (&r)[4], char* dst) {
; #pragma unroll
;   for (int i = 0; i < 4; ++i) { const int idx = tid + 256 * i, row = idx >> 4, ch = idx & 15; *(u32x4*)(dst + koff(row, ch)) = r[i]; }
; }
; DI void sts_tile_v(int tid, const u32x4 (&r)[4], char* dst) {
; #pragma unroll
;   for (int i = 0; i < 4; ++i) { const int idx = tid + 256 * i, row = idx >> 4, ch = idx & 15; *(u32x4*)(dst + voff(row, ch)) = r[i]; }
; }
; template <int QS>
; DI void nsa_cmpwin_item(int item, const bf16_t* __restrict__ z, const bf16_t* __restrict__ kcmp, const bf16_t* __restrict__ vcmp,
;                                 const float* __restrict__ bgate, float* __restrict__ P, float* __restrict__ part, char* smem) {
;     ...
;     for (int j = j0; j <= j1; ++j) {
;       __syncthreads();
;       load_tile_k(tid, z + (tb + j * 64) * NSP + NKW + grp * 128, NSP, Ks);
;       load_tile_v(tid, z + (tb + j * 64) * NSP + NVW + grp * 128, NSP, Vs);
;       __syncthreads();
;       f32x4 s[4][QS];
; #pragma unroll
;       for (int kt = 0; kt < 4; ++kt)
; #pragma unroll
;         for (int qs = 0; qs < QS; ++qs) s[kt][qs] = (f32x4){0.f, 0.f, 0.f, 0.f};
;       qk_tile<4, QS>(Ks, qf, 0, s, lane);
;       softmax_tile<AM_WIN, QS>(s, o, m, l, qi, qm, j * 64, 0, sc, lane, (j * 64 + 63 <= q0) && (j * 64 > q0 + QB - 1 - 512));
.LBB0_487:
	s_ashr_i32 s0, s11, 31
	s_add_u32 s1, s68, s11
	s_addc_u32 s0, s69, s0
	s_mulk_i32 s0, 0x2900
	s_mul_hi_u32 s4, s1, 0x2900
	s_add_i32 s4, s4, s0
	s_mulk_i32 s1, 0x2900
	s_add_u32 s0, s86, s1
	s_addc_u32 s1, s87, s4
	s_add_u32 s0, s0, s12
	s_addc_u32 s1, s1, 0
	v_lshl_add_u64 v[114:115], s[0:1], 0, v[0:1]
	s_mov_b64 s[0:1], 0x2000
	v_lshl_add_u64 v[110:111], v[114:115], 0, s[0:1]
	v_lshl_add_u64 v[98:99], v[110:111], 0, v[134:135]
	s_barrier
	global_load_dwordx4 v[98:101], v[98:99], off
	v_lshl_add_u64 v[102:103], v[110:111], 0, v[136:137]
	global_load_dwordx4 v[102:105], v[102:103], off
	v_lshl_add_u64 v[106:107], v[110:111], 0, v[146:147]
	global_load_dwordx4 v[106:109], v[106:107], off
	v_lshl_add_u64 v[110:111], v[110:111], 0, v[152:153]
	global_load_dwordx4 v[110:113], v[110:111], off
	s_mov_b64 s[0:1], 0x2400
	s_mov_b64 s[6:7], -1
	v_lshl_add_u64 v[158:159], v[114:115], 0, s[0:1]
	v_lshl_add_u64 v[116:117], v[158:159], 0, v[134:135]
	global_load_dwordx4 v[116:119], v[116:117], off
	v_lshl_add_u64 v[120:121], v[158:159], 0, v[136:137]
	global_load_dwordx4 v[120:123], v[120:121], off
	v_lshl_add_u64 v[124:125], v[158:159], 0, v[146:147]
	global_load_dwordx4 v[124:127], v[124:125], off
	v_lshl_add_u64 v[154:155], v[158:159], 0, v[152:153]
	global_load_dwordx4 v[154:157], v[154:155], off
	s_waitcnt vmcnt(7)
	ds_write_b128 v172, v[98:101]
	s_waitcnt vmcnt(6)
	ds_write_b128 v173, v[102:105]
	s_waitcnt vmcnt(5)
	ds_write_b128 v174, v[106:109]
	s_waitcnt vmcnt(4)
	ds_write_b128 v175, v[110:113]
	s_nop 0
	s_add_i32 s0, s11, 63
	s_cmp_le_i32 s0, s71
	s_cselect_b64 s[0:1], -1, 0
	s_cmp_gt_i32 s11, s9
	s_cselect_b64 s[4:5], -1, 0
	s_and_b64 s[4:5], s[0:1], s[4:5]
	s_and_b64 vcc, exec, s[4:5]
	s_waitcnt vmcnt(3)
	ds_write_b128 v176, v[116:119] offset:16384
	s_waitcnt vmcnt(2)
	ds_write_b128 v177, v[120:123] offset:16384
	s_waitcnt vmcnt(1)
	ds_write_b128 v178, v[124:127] offset:16384
	s_waitcnt vmcnt(0)
	ds_write_b128 v179, v[154:157] offset:16384
	s_waitcnt lgkmcnt(0)
	s_barrier
	ds_read_b128 v[98:101], v182
	ds_read_b128 v[106:109], v182 offset:4096
	ds_read_b128 v[154:157], v183
	s_waitcnt lgkmcnt(2)
	v_mfma_f32_16x16x32_bf16 v[102:105], v[98:101], v[2:5], 0
	ds_read_b128 v[114:117], v182 offset:8192
	ds_read_b128 v[122:125], v182 offset:12288
	v_mfma_f32_16x16x32_bf16 v[98:101], v[98:101], v[18:21], 0
	s_waitcnt lgkmcnt(2)
	v_mfma_f32_16x16x32_bf16 v[102:105], v[154:157], v[6:9], v[102:105]
	v_mfma_f32_16x16x32_bf16 v[98:101], v[154:157], v[22:25], v[98:101]
	ds_read_b128 v[154:157], v183 offset:4096
	v_mfma_f32_16x16x32_bf16 v[110:113], v[106:109], v[2:5], 0
	v_mfma_f32_16x16x32_bf16 v[106:109], v[106:109], v[18:21], 0
	s_waitcnt lgkmcnt(0)
	v_mfma_f32_16x16x32_bf16 v[110:113], v[154:157], v[6:9], v[110:113]
	v_mfma_f32_16x16x32_bf16 v[106:109], v[154:157], v[22:25], v[106:109]
	ds_read_b128 v[154:157], v183 offset:8192
	v_mfma_f32_16x16x32_bf16 v[118:121], v[114:117], v[2:5], 0
	v_mfma_f32_16x16x32_bf16 v[114:117], v[114:117], v[18:21], 0
	s_waitcnt lgkmcnt(0)
	v_mfma_f32_16x16x32_bf16 v[118:121], v[154:157], v[6:9], v[118:121]
	v_mfma_f32_16x16x32_bf16 v[114:117], v[154:157], v[22:25], v[114:117]
	ds_read_b128 v[154:157], v183 offset:12288
	v_mfma_f32_16x16x32_bf16 v[126:129], v[122:125], v[2:5], 0
	v_mfma_f32_16x16x32_bf16 v[122:125], v[122:125], v[18:21], 0
	s_waitcnt lgkmcnt(0)
	v_mfma_f32_16x16x32_bf16 v[126:129], v[154:157], v[6:9], v[126:129]
	v_mfma_f32_16x16x32_bf16 v[122:125], v[154:157], v[22:25], v[122:125]
	ds_read_b128 v[154:157], v184
	s_waitcnt lgkmcnt(0)
	v_mfma_f32_16x16x32_bf16 v[102:105], v[154:157], v[10:13], v[102:105]
	v_mfma_f32_16x16x32_bf16 v[98:101], v[154:157], v[26:29], v[98:101]
	ds_read_b128 v[154:157], v184 offset:4096
	s_waitcnt lgkmcnt(0)
	v_mfma_f32_16x16x32_bf16 v[158:161], v[154:157], v[10:13], v[110:113]
	s_nop 2
	ds_read_b128 v[110:113], v184 offset:8192
	s_waitcnt lgkmcnt(0)
	v_mfma_f32_16x16x32_bf16 v[118:121], v[110:113], v[10:13], v[118:121]
	v_mfma_f32_16x16x32_bf16 v[114:117], v[110:113], v[26:29], v[114:117]
	ds_read_b128 v[110:113], v184 offset:12288
	v_mfma_f32_16x16x32_bf16 v[106:109], v[154:157], v[26:29], v[106:109]
	s_waitcnt lgkmcnt(0)
	v_mfma_f32_16x16x32_bf16 v[154:157], v[110:113], v[10:13], v[126:129]
	v_mfma_f32_16x16x32_bf16 v[162:165], v[110:113], v[26:29], v[122:125]
	ds_read_b128 v[110:113], v185
	s_waitcnt lgkmcnt(0)
	v_mfma_f32_16x16x32_bf16 v[126:129], v[110:113], v[14:17], v[102:105]
	v_mfma_f32_16x16x32_bf16 v[110:113], v[110:113], v[30:33], v[98:101]
	s_nop 2
	ds_read_b128 v[98:101], v185 offset:4096
	s_waitcnt lgkmcnt(0)
	v_mfma_f32_16x16x32_bf16 v[122:125], v[98:101], v[14:17], v[158:161]
	v_mfma_f32_16x16x32_bf16 v[106:109], v[98:101], v[30:33], v[106:109]
	ds_read_b128 v[98:101], v185 offset:8192
	s_waitcnt lgkmcnt(0)
	v_mfma_f32_16x16x32_bf16 v[118:121], v[98:101], v[14:17], v[118:121]
	v_mfma_f32_16x16x32_bf16 v[102:105], v[98:101], v[30:33], v[114:117]
	ds_read_b128 v[98:101], v185 offset:12288
	s_waitcnt lgkmcnt(0)
	v_mfma_f32_16x16x32_bf16 v[114:117], v[98:101], v[14:17], v[154:157]
	s_nop 2
	v_add_u32_e32 v154, s11, v208
	v_cmp_le_i32_e64 s[0:1], v154, v142
	v_add_u32_e32 v224, 2, v154
	v_mfma_f32_16x16x32_bf16 v[98:101], v[98:101], v[30:33], v[162:165]
	v_add_u32_e32 v221, 3, v154
	v_add_u32_e32 v222, 16, v154
	v_add_u32_e32 v218, 17, v154
	v_add_u32_e32 v216, 18, v154
	v_add_u32_e32 v228, 19, v154
	v_add_u32_e32 v227, 32, v154
	v_add_u32_e32 v226, 33, v154
	v_add_u32_e32 v225, 34, v154
	v_add_u32_e32 v223, 35, v154
	v_add_u32_e32 v220, 48, v154
	v_add_u32_e32 v219, 49, v154
	v_add_u32_e32 v217, 50, v154
	v_add_u32_e32 v215, 51, v154
	s_cbranch_vccnz .LBB0_489
; template <int MODE, int QS>
; DI void softmax_tile(f32x4 (&s)[4][QS], f32x4 (&o)[QS][8], float (&m)[QS], float (&l)[QS], const int (&qi)[QS], const unsigned (&qmask)[QS],
;                      int kbase, int tilebit, float sc, int lane, bool interior) {
;     ...
; #pragma unroll
;       for (int kt = 0; kt < 4; ++kt)
; #pragma unroll
;         for (int r = 0; r < 4; ++r) {
;           const int kj = kbase + kt * 16 + 4 * g + r;
;           bool v = kj <= qi[qs];
;           if (MODE == AM_WIN) v = v && (kj > qi[qs] - 512);
;           if (MODE == AM_SEL) v = v && ((qmask[qs] >> tilebit) & 1u);
;           const float x = v ? s[kt][qs][r] * sc : -1e30f;
;           s[kt][qs][r] = x;
;           mx = fmaxf(mx, x);
;         }
;     }
	v_cmp_gt_i32_e32 vcc, v154, v209
	v_mul_f32_e32 v155, 0x3e0293ee, v126
	s_and_b64 vcc, s[0:1], vcc
	v_cndmask_b32_e32 v156, v199, v155, vcc
	v_cmp_lt_i32_e32 vcc, v154, v142
	v_cmp_ge_i32_e64 s[0:1], v154, v209
	v_mul_f32_e32 v155, 0x3e0293ee, v127
	s_and_b64 vcc, vcc, s[0:1]
	v_cndmask_b32_e32 v157, v199, v155, vcc
	v_cmp_le_i32_e32 vcc, v224, v142
	v_cmp_gt_i32_e64 s[0:1], v224, v209
	v_mul_f32_e32 v158, 0x3e0293ee, v128
	s_and_b64 vcc, vcc, s[0:1]
	v_cndmask_b32_e32 v158, v199, v158, vcc
	v_cmp_le_i32_e32 vcc, v221, v142
	v_cmp_gt_i32_e64 s[0:1], v221, v209
	v_mul_f32_e32 v159, 0x3e0293ee, v129
	s_and_b64 vcc, vcc, s[0:1]
	v_cndmask_b32_e32 v159, v199, v159, vcc
	v_cmp_le_i32_e32 vcc, v222, v142
	v_cmp_gt_i32_e64 s[0:1], v222, v209
	v_mul_f32_e32 v160, 0x3e0293ee, v122
	s_and_b64 vcc, vcc, s[0:1]
	v_cndmask_b32_e32 v160, v199, v160, vcc
	v_cmp_le_i32_e32 vcc, v218, v142
	v_cmp_gt_i32_e64 s[0:1], v218, v209
	v_mul_f32_e32 v161, 0x3e0293ee, v123
	s_and_b64 vcc, vcc, s[0:1]
	v_cndmask_b32_e32 v161, v199, v161, vcc
	v_cmp_le_i32_e32 vcc, v216, v142
	v_cmp_gt_i32_e64 s[0:1], v216, v209
	v_mul_f32_e32 v162, 0x3e0293ee, v124
	s_and_b64 vcc, vcc, s[0:1]
	v_cndmask_b32_e32 v162, v199, v162, vcc
	v_cmp_le_i32_e32 vcc, v228, v142
	v_cmp_gt_i32_e64 s[0:1], v228, v209
	v_mul_f32_e32 v163, 0x3e0293ee, v125
	s_and_b64 vcc, vcc, s[0:1]
	v_cndmask_b32_e32 v163, v199, v163, vcc
	v_cmp_le_i32_e32 vcc, v227, v142
	v_cmp_gt_i32_e64 s[0:1], v227, v209
	v_mul_f32_e32 v164, 0x3e0293ee, v118
	s_and_b64 vcc, vcc, s[0:1]
	v_cndmask_b32_e32 v164, v199, v164, vcc
	v_cmp_le_i32_e32 vcc, v226, v142
	v_cmp_gt_i32_e64 s[0:1], v226, v209
	v_mul_f32_e32 v165, 0x3e0293ee, v119
	s_and_b64 vcc, vcc, s[0:1]
	v_cndmask_b32_e32 v165, v199, v165, vcc
	v_cmp_le_i32_e32 vcc, v225, v142
	v_cmp_gt_i32_e64 s[0:1], v225, v209
	v_mul_f32_e32 v166, 0x3e0293ee, v120
	s_and_b64 vcc, vcc, s[0:1]
	v_cndmask_b32_e32 v166, v199, v166, vcc
	v_cmp_le_i32_e32 vcc, v223, v142
	v_cmp_gt_i32_e64 s[0:1], v223, v209
	v_mul_f32_e32 v167, 0x3e0293ee, v121
	s_and_b64 vcc, vcc, s[0:1]
	v_cndmask_b32_e32 v167, v199, v167, vcc
	v_cmp_le_i32_e32 vcc, v220, v142
	v_cmp_gt_i32_e64 s[0:1], v220, v209
	v_mul_f32_e32 v168, 0x3e0293ee, v114
	s_and_b64 vcc, vcc, s[0:1]
	v_max3_f32 v155, v156, s83, v157
	v_cndmask_b32_e32 v168, v199, v168, vcc
	v_cmp_le_i32_e32 vcc, v219, v142
	v_cmp_gt_i32_e64 s[0:1], v219, v209
	v_max3_f32 v155, v155, v158, v159
	v_mul_f32_e32 v169, 0x3e0293ee, v115
	s_and_b64 vcc, vcc, s[0:1]
	v_max3_f32 v155, v155, v160, v161
	v_cndmask_b32_e32 v169, v199, v169, vcc
	v_cmp_le_i32_e32 vcc, v217, v142
	v_cmp_gt_i32_e64 s[0:1], v217, v209
	v_max3_f32 v155, v155, v162, v163
	v_mul_f32_e32 v170, 0x3e0293ee, v116
	s_and_b64 vcc, vcc, s[0:1]
	v_max3_f32 v155, v155, v164, v165
	v_cndmask_b32_e32 v170, v199, v170, vcc
	v_cmp_le_i32_e32 vcc, v215, v142
	v_cmp_gt_i32_e64 s[0:1], v215, v209
	v_max3_f32 v155, v155, v166, v167
	v_mul_f32_e32 v171, 0x3e0293ee, v117
	s_and_b64 vcc, vcc, s[0:1]
	v_max3_f32 v155, v155, v168, v169
	v_cndmask_b32_e32 v171, v199, v171, vcc
	v_max3_f32 v155, v155, v170, v171
	s_mov_b64 s[6:7], 0

; DI void load_tile_k(int tid, const bf16_t* __restrict__ g, int ld, char* dst) { u32x4 r[4]; ldg_tile(tid, g, ld, r); sts_tile_k(tid, r, dst); }
; DI void load_tile_v(int tid, const bf16_t* __restrict__ g, int ld, char* dst) { u32x4 r[4]; ldg_tile(tid, g, ld, r); sts_tile_v(tid, r, dst); }
; template <int MODE, int QS>
; DI void softmax_tile(f32x4 (&s)[4][QS], f32x4 (&o)[QS][8], float (&m)[QS], float (&l)[QS], const int (&qi)[QS], const unsigned (&qmask)[QS],
;                      int kbase, int tilebit, float sc, int lane, bool interior) {
;     ...
;       float sce = sc, bias = 0.f;
;       if (MODE == AM_SEL) { const bool on = (qmask[qs] >> tilebit) & 1u; sce = on ? sc : 0.f; bias = on ? 0.f : -1e30f; }
; #pragma unroll
;       for (int kt = 0; kt < 4; ++kt)
; #pragma unroll
;         for (int r = 0; r < 4; ++r) { const float x = fmaf(s[kt][qs][r], sce, bias); s[kt][qs][r] = x; mx = fmaxf(mx, x); }
; template <int QS>
; DI void nsa_sel_item(int item, const bf16_t* __restrict__ z, const unsigned* __restrict__ sel, const float* __restrict__ bgate,
;                              const float* __restrict__ part, bf16_t* __restrict__ mix, char* smem) {
;     ...
; #pragma unroll 1
;   while (rem) {
;     const int j = __builtin_ctz(rem);
;     rem &= rem - 1u;
;     __syncthreads();
;     load_tile_k(tid, z + (tb + j * 64) * NSP + NKS + grp * 128, NSP, Ks);
;     load_tile_v(tid, z + (tb + j * 64) * NSP + NVS + grp * 128, NSP, Vs);
;     __syncthreads();
;     f32x4 s[4][QS];
; #pragma unroll
;     for (int kt = 0; kt < 4; ++kt)
; #pragma unroll
;       for (int qs = 0; qs < QS; ++qs) s[kt][qs] = (f32x4){0.f, 0.f, 0.f, 0.f};
;     qk_tile<4, QS>(Ks, qf, 0, s, lane);
;     softmax_tile<AM_SEL, QS>(s, o, m, l, qi, qm, j * 64, j, sc, lane, j * 64 + 63 <= q0);
.LBB0_616:
	s_ff1_i32_b32 s0, s30
	s_lshl_b32 s4, s0, 6
	s_or_b32 s1, s4, s96
	s_mulk_i32 s1, 0x2900
	s_add_u32 s1, s86, s1
	s_addc_u32 s3, s87, 0
	s_add_u32 s2, s1, s31
	s_addc_u32 s3, s3, 0
	v_lshl_add_u64 v[114:115], s[2:3], 0, v[0:1]
	s_mov_b64 s[2:3], 0x1800
	v_lshl_add_u64 v[110:111], v[114:115], 0, s[2:3]
	v_lshl_add_u64 v[98:99], v[110:111], 0, v[138:139]
	s_barrier
	global_load_dwordx4 v[98:101], v[98:99], off
	v_lshl_add_u64 v[102:103], v[110:111], 0, v[140:141]
	global_load_dwordx4 v[102:105], v[102:103], off
	v_lshl_add_u64 v[106:107], v[110:111], 0, v[142:143]
	global_load_dwordx4 v[106:109], v[106:107], off
	v_lshl_add_u64 v[110:111], v[110:111], 0, v[144:145]
	global_load_dwordx4 v[110:113], v[110:111], off
	s_mov_b64 s[2:3], 0x1c00
	v_lshl_add_u64 v[158:159], v[114:115], 0, s[2:3]
	v_lshl_add_u64 v[116:117], v[158:159], 0, v[138:139]
	global_load_dwordx4 v[116:119], v[116:117], off
	v_lshl_add_u64 v[120:121], v[158:159], 0, v[140:141]
	global_load_dwordx4 v[120:123], v[120:121], off
	v_lshl_add_u64 v[124:125], v[158:159], 0, v[142:143]
	global_load_dwordx4 v[124:127], v[124:125], off
	v_lshl_add_u64 v[152:153], v[158:159], 0, v[144:145]
	global_load_dwordx4 v[152:155], v[152:153], off
	s_or_b32 s1, s4, 63
	s_cmp_le_i32 s1, s29
	s_cselect_b64 s[24:25], -1, 0
	s_lshl_b32 s33, 1, s0
	v_and_b32_e32 v167, s33, v172
	s_and_b64 vcc, exec, s[24:25]
	v_cmp_eq_u32_e64 s[0:1], 0, v167
	s_waitcnt vmcnt(7)
	ds_write_b128 v179, v[98:101]
	s_waitcnt vmcnt(6)
	ds_write_b128 v180, v[102:105]
	s_waitcnt vmcnt(5)
	ds_write_b128 v181, v[106:109]
	s_waitcnt vmcnt(4)
	ds_write_b128 v182, v[110:113]
	s_nop 0
	s_mov_b64 s[2:3], -1
	s_waitcnt vmcnt(3)
	ds_write_b128 v183, v[116:119] offset:16384
	s_waitcnt vmcnt(2)
	ds_write_b128 v184, v[120:123] offset:16384
	s_waitcnt vmcnt(1)
	ds_write_b128 v185, v[124:127] offset:16384
	s_waitcnt vmcnt(0)
	ds_write_b128 v186, v[152:155] offset:16384
	s_waitcnt lgkmcnt(0)
	s_barrier
	ds_read_b128 v[98:101], v187
	ds_read_b128 v[106:109], v187 offset:4096
	ds_read_b128 v[152:155], v188
	s_waitcnt lgkmcnt(2)
	v_mfma_f32_16x16x32_bf16 v[102:105], v[98:101], v[62:65], 0
	ds_read_b128 v[114:117], v187 offset:8192
	ds_read_b128 v[122:125], v187 offset:12288
	v_mfma_f32_16x16x32_bf16 v[98:101], v[98:101], v[78:81], 0
	s_waitcnt lgkmcnt(2)
	v_mfma_f32_16x16x32_bf16 v[102:105], v[152:155], v[66:69], v[102:105]
	v_mfma_f32_16x16x32_bf16 v[98:101], v[152:155], v[82:85], v[98:101]
	ds_read_b128 v[152:155], v188 offset:4096
	v_mfma_f32_16x16x32_bf16 v[110:113], v[106:109], v[62:65], 0
	v_mfma_f32_16x16x32_bf16 v[106:109], v[106:109], v[78:81], 0
	s_waitcnt lgkmcnt(0)
	v_mfma_f32_16x16x32_bf16 v[110:113], v[152:155], v[66:69], v[110:113]
	v_mfma_f32_16x16x32_bf16 v[106:109], v[152:155], v[82:85], v[106:109]
	ds_read_b128 v[152:155], v188 offset:8192
	v_mfma_f32_16x16x32_bf16 v[118:121], v[114:117], v[62:65], 0
	v_mfma_f32_16x16x32_bf16 v[114:117], v[114:117], v[78:81], 0
	s_waitcnt lgkmcnt(0)
	v_mfma_f32_16x16x32_bf16 v[118:121], v[152:155], v[66:69], v[118:121]
	v_mfma_f32_16x16x32_bf16 v[114:117], v[152:155], v[82:85], v[114:117]
	ds_read_b128 v[152:155], v188 offset:12288
	v_mfma_f32_16x16x32_bf16 v[126:129], v[122:125], v[62:65], 0
	v_mfma_f32_16x16x32_bf16 v[122:125], v[122:125], v[78:81], 0
	s_waitcnt lgkmcnt(0)
	v_mfma_f32_16x16x32_bf16 v[126:129], v[152:155], v[66:69], v[126:129]
	v_mfma_f32_16x16x32_bf16 v[122:125], v[152:155], v[82:85], v[122:125]
	ds_read_b128 v[152:155], v189
	s_waitcnt lgkmcnt(0)
	v_mfma_f32_16x16x32_bf16 v[102:105], v[152:155], v[70:73], v[102:105]
	v_mfma_f32_16x16x32_bf16 v[98:101], v[152:155], v[86:89], v[98:101]
	ds_read_b128 v[152:155], v189 offset:4096
	s_waitcnt lgkmcnt(0)
	v_mfma_f32_16x16x32_bf16 v[156:159], v[152:155], v[70:73], v[110:113]
	s_nop 2
	ds_read_b128 v[110:113], v189 offset:8192
	s_waitcnt lgkmcnt(0)
	v_mfma_f32_16x16x32_bf16 v[118:121], v[110:113], v[70:73], v[118:121]
	v_mfma_f32_16x16x32_bf16 v[114:117], v[110:113], v[86:89], v[114:117]
	ds_read_b128 v[110:113], v189 offset:12288
	v_mfma_f32_16x16x32_bf16 v[106:109], v[152:155], v[86:89], v[106:109]
	s_waitcnt lgkmcnt(0)
	v_mfma_f32_16x16x32_bf16 v[152:155], v[110:113], v[70:73], v[126:129]
	v_mfma_f32_16x16x32_bf16 v[160:163], v[110:113], v[86:89], v[122:125]
	ds_read_b128 v[110:113], v205
	s_waitcnt lgkmcnt(0)
	v_mfma_f32_16x16x32_bf16 v[126:129], v[110:113], v[74:77], v[102:105]
	v_mfma_f32_16x16x32_bf16 v[110:113], v[110:113], v[90:93], v[98:101]
	s_nop 2
	ds_read_b128 v[98:101], v205 offset:4096
	s_waitcnt lgkmcnt(0)
	v_mfma_f32_16x16x32_bf16 v[122:125], v[98:101], v[74:77], v[156:159]
	v_mfma_f32_16x16x32_bf16 v[106:109], v[98:101], v[90:93], v[106:109]
	ds_read_b128 v[98:101], v205 offset:8192
	s_waitcnt lgkmcnt(0)
	v_mfma_f32_16x16x32_bf16 v[118:121], v[98:101], v[74:77], v[118:121]
	v_mfma_f32_16x16x32_bf16 v[102:105], v[98:101], v[90:93], v[114:117]
	ds_read_b128 v[98:101], v205 offset:12288
	s_waitcnt lgkmcnt(0)
	v_mfma_f32_16x16x32_bf16 v[114:117], v[98:101], v[74:77], v[152:155]
	v_mfma_f32_16x16x32_bf16 v[98:101], v[98:101], v[90:93], v[160:163]
	s_cbranch_vccz .LBB0_618
	v_cndmask_b32_e64 v164, v201, 0, s[0:1]
	v_cndmask_b32_e64 v218, 0, v199, s[0:1]
	v_pk_fma_f32 v[152:153], v[126:127], v[164:165], v[218:219] op_sel_hi:[1,0,0]
	v_pk_fma_f32 v[146:147], v[128:129], v[164:165], v[218:219] op_sel_hi:[1,0,0]
	v_max3_f32 v154, v152, s83, v153
	v_max3_f32 v154, v154, v146, v147
	v_pk_fma_f32 v[156:157], v[122:123], v[164:165], v[218:219] op_sel_hi:[1,0,0]
	s_mov_b64 s[2:3], 0
	v_max3_f32 v158, v154, v156, v157
	v_pk_fma_f32 v[154:155], v[124:125], v[164:165], v[218:219] op_sel_hi:[1,0,0]
	s_nop 0
	v_max3_f32 v160, v158, v154, v155
	v_pk_fma_f32 v[158:159], v[118:119], v[164:165], v[218:219] op_sel_hi:[1,0,0]
	s_nop 0
	v_max3_f32 v162, v160, v158, v159
	v_pk_fma_f32 v[160:161], v[120:121], v[164:165], v[218:219] op_sel_hi:[1,0,0]
	s_nop 0
	v_max3_f32 v165, v162, v160, v161
	v_pk_fma_f32 v[162:163], v[114:115], v[164:165], v[218:219] op_sel_hi:[1,0,0]
	s_nop 0
	v_max3_f32 v217, v165, v162, v163
	v_pk_fma_f32 v[164:165], v[116:117], v[164:165], v[218:219] op_sel_hi:[1,0,0]
	s_nop 0
	v_max3_f32 v228, v217, v164, v165

; DI void load_tile_k(int tid, const bf16_t* __restrict__ g, int ld, char* dst) { u32x4 r[4]; ldg_tile(tid, g, ld, r); sts_tile_k(tid, r, dst); }
; DI void load_tile_v(int tid, const bf16_t* __restrict__ g, int ld, char* dst) { u32x4 r[4]; ldg_tile(tid, g, ld, r); sts_tile_v(tid, r, dst); }
; DI void ldg_tile(int tid, const bf16_t* __restrict__ g, int ld, u32x4 (&r)[4]) {
; #pragma unroll
;   for (int i = 0; i < 4; ++i) { const int idx = tid + 256 * i, row = idx >> 4, ch = idx & 15; r[i] = *(const u32x4*)(g + (size_t)row * ld + ch * 8); }
; }
; DI void sts_tile_k(int tid, const u32x4 (&r)[4], char* dst) {
; #pragma unroll
;   for (int i = 0; i < 4; ++i) { const int idx = tid + 256 * i, row = idx >> 4, ch = idx & 15; *(u32x4*)(dst + koff(row, ch)) = r[i]; }
; }
; DI void sts_tile_v(int tid, const u32x4 (&r)[4], char* dst) {
; #pragma unroll
;   for (int i = 0; i < 4; ++i) { const int idx = tid + 256 * i, row = idx >> 4, ch = idx & 15; *(u32x4*)(dst + voff(row, ch)) = r[i]; }
; }
; DI void ldg_tile_k2(int tid, const bf16_t* __restrict__ g, int ld, u32x4 (&r)[2]) {
; #pragma unroll
;   for (int i = 0; i < 2; ++i) { const int idx = tid + 256 * i, row = idx >> 3, ch = idx & 7; r[i] = *(const u32x4*)(g + (size_t)row * ld + ch * 8); }
; }
; DI void sts_tile_k2(int tid, const u32x4 (&r)[2], char* dst) {
; #pragma unroll
;   for (int i = 0; i < 2; ++i) { const int idx = tid + 256 * i, row = idx >> 3, ch = idx & 7; *(u32x4*)(dst + k2off(row, ch)) = r[i]; }
; }
; template <int QS>
; DI void mla_attn_item(int item, const bf16_t* __restrict__ q, const bf16_t* __restrict__ kv, const bf16_t* __restrict__ krope,
;                               const int* __restrict__ pos, bf16_t* __restrict__ mix, char* smem) {
;     ...
;     __syncthreads();
;     load_tile_k(tid, kv + (tb + j * 64) * 2048 + h * 256, 2048, Ks);
;     load_tile_v(tid, kv + (tb + j * 64) * 2048 + h * 256 + 128, 2048, Vs);
;     { u32x4 r2[2]; ldg_tile_k2(tid, krope + (tb + j * 64) * 64, 64, r2); sts_tile_k2(tid, r2, K2s); }
;     __syncthreads();
.LBB0_965:
	v_lshl_add_u64 v[2:3], s[90:91], 0, v[174:175]
	s_mov_b32 s0, 0x2e120000
	v_add_co_u32_e32 v2, vcc, s0, v2
	v_lshl_add_u64 v[120:121], s[90:91], 0, v[172:173]
	s_nop 0
	v_addc_co_u32_e32 v3, vcc, 0, v3, vcc
	v_add_co_u32_e32 v132, vcc, s0, v120
	v_lshl_add_u64 v[124:125], s[90:91], 0, v[170:171]
	s_nop 0
	v_addc_co_u32_e32 v133, vcc, 0, v121, vcc
	v_add_co_u32_e32 v134, vcc, s0, v124
	s_barrier
	global_load_dwordx4 v[116:119], v[2:3], off
	global_load_dwordx4 v[120:123], v[132:133], off
	v_addc_co_u32_e32 v135, vcc, 0, v125, vcc
	v_lshl_add_u64 v[128:129], s[90:91], 0, v[168:169]
	v_add_co_u32_e32 v136, vcc, s0, v128
	global_load_dwordx4 v[124:127], v[134:135], off
	s_nop 0
	v_addc_co_u32_e32 v137, vcc, 0, v129, vcc
	global_load_dwordx4 v[128:131], v[136:137], off
	global_load_dwordx4 v[138:141], v[2:3], off offset:256
	global_load_dwordx4 v[142:145], v[132:133], off offset:256
	global_load_dwordx4 v[176:179], v[134:135], off offset:256
	global_load_dwordx4 v[180:183], v[136:137], off offset:256
	v_lshl_add_u64 v[146:147], s[90:91], 0, v[164:165]
	global_load_dwordx4 v[184:187], v[146:147], off
	v_lshl_add_u64 v[238:239], s[90:91], 0, v[166:167]
	global_load_dwordx4 v[234:237], v[238:239], off
	s_add_i32 s0, s5, 63
	s_cmp_le_i32 s0, s14
	s_cselect_b64 s[8:9], -1, 0
	s_mov_b64 s[0:1], -1
	s_and_b64 vcc, exec, s[8:9]
	s_waitcnt vmcnt(9)
	ds_write_b128 v206, v[116:119]
	s_waitcnt vmcnt(8)
	ds_write_b128 v207, v[120:123]
	s_waitcnt vmcnt(7)
	ds_write_b128 v208, v[124:127]
	s_waitcnt vmcnt(6)
	ds_write_b128 v209, v[128:131]
	s_nop 0
	s_waitcnt vmcnt(5)
	ds_write_b128 v210, v[138:141] offset:16384
	s_waitcnt vmcnt(4)
	ds_write_b128 v211, v[142:145] offset:16384
	s_waitcnt vmcnt(3)
	ds_write_b128 v212, v[176:179] offset:16384
	s_waitcnt vmcnt(2)
	ds_write_b128 v213, v[180:183] offset:16384
	s_nop 0
	s_waitcnt vmcnt(1)
	ds_write_b128 v214, v[184:187] offset:32768
	s_waitcnt vmcnt(0)
	ds_write_b128 v215, v[234:237] offset:32768
	s_waitcnt lgkmcnt(0)
	s_barrier
; template <int NKS, int QS>
; DI void qk_tile(const char* Ks, const bf16x8 (&qf)[QS][6], int ks0, f32x4 (&s)[4][QS], int lane) {
; #pragma unroll
;   for (int ks = 0; ks < NKS; ++ks)
; #pragma unroll
;     for (int kt = 0; kt < 4; ++kt) {
;       const bf16x8 kf = *(const bf16x8*)(Ks + koff(kt * 16 + (lane & 15), ks * 4 + (lane >> 4)));
; #pragma unroll
;       for (int qs = 0; qs < QS; ++qs) s[kt][qs] = __builtin_amdgcn_mfma_f32_16x16x32_bf16(kf, qf[qs][ks0 + ks], s[kt][qs], 0, 0, 0);
;     }
; }
; template <int QS>
; DI void qk_tile2(const char* K2s, const bf16x8 (&qf)[QS][6], f32x4 (&s)[4][QS], int lane) {
; #pragma unroll
;   for (int ks = 0; ks < 2; ++ks)
; #pragma unroll
;     for (int kt = 0; kt < 4; ++kt) {
;       const bf16x8 kf = *(const bf16x8*)(K2s + k2off(kt * 16 + (lane & 15), ks * 4 + (lane >> 4)));
; #pragma unroll
;       for (int qs = 0; qs < QS; ++qs) s[kt][qs] = __builtin_amdgcn_mfma_f32_16x16x32_bf16(kf, qf[qs][4 + ks], s[kt][qs], 0, 0, 0);
;     }
; }
; template <int MODE, int QS>
; DI void softmax_tile(f32x4 (&s)[4][QS], f32x4 (&o)[QS][8], float (&m)[QS], float (&l)[QS], const int (&qi)[QS], const unsigned (&qmask)[QS],
;                      int kbase, int tilebit, float sc, int lane, bool interior) {
;     ...
;       float sce = sc, bias = 0.f;
;       if (MODE == AM_SEL) { const bool on = (qmask[qs] >> tilebit) & 1u; sce = on ? sc : 0.f; bias = on ? 0.f : -1e30f; }
; #pragma unroll
;       for (int kt = 0; kt < 4; ++kt)
; #pragma unroll
;         for (int r = 0; r < 4; ++r) { const float x = fmaf(s[kt][qs][r], sce, bias); s[kt][qs][r] = x; mx = fmaxf(mx, x); }
; template <int QS>
; DI void mla_attn_item(int item, const bf16_t* __restrict__ q, const bf16_t* __restrict__ kv, const bf16_t* __restrict__ krope,
;                               const int* __restrict__ pos, bf16_t* __restrict__ mix, char* smem) {
;     ...
;     qk_tile<4, QS>(Ks, qf, 0, s, lane);
;     qk_tile2<QS>(K2s, qf, s, lane);
;     softmax_tile<AM_MLA, QS>(s, o, m, l, qi, qm, j * 64, 0, sc, lane, j * 64 + 63 <= q0);
	ds_read_b128 v[116:119], v216
	ds_read_b128 v[124:127], v216 offset:4096
	ds_read_b128 v[176:179], v217
	s_waitcnt lgkmcnt(2)
	v_mfma_f32_16x16x32_bf16 v[120:123], v[116:119], v[4:7], 0
	ds_read_b128 v[132:135], v216 offset:8192
	ds_read_b128 v[140:143], v216 offset:12288
	v_mfma_f32_16x16x32_bf16 v[116:119], v[116:119], v[20:23], 0
	s_waitcnt lgkmcnt(2)
	v_mfma_f32_16x16x32_bf16 v[120:123], v[176:179], v[8:11], v[120:123]
	v_mfma_f32_16x16x32_bf16 v[116:119], v[176:179], v[24:27], v[116:119]
	ds_read_b128 v[176:179], v217 offset:4096
	v_mfma_f32_16x16x32_bf16 v[128:131], v[124:127], v[4:7], 0
	v_mfma_f32_16x16x32_bf16 v[124:127], v[124:127], v[20:23], 0
	s_waitcnt lgkmcnt(0)
	v_mfma_f32_16x16x32_bf16 v[128:131], v[176:179], v[8:11], v[128:131]
	v_mfma_f32_16x16x32_bf16 v[124:127], v[176:179], v[24:27], v[124:127]
	ds_read_b128 v[176:179], v217 offset:8192
	v_mfma_f32_16x16x32_bf16 v[136:139], v[132:135], v[4:7], 0
	v_mfma_f32_16x16x32_bf16 v[132:135], v[132:135], v[20:23], 0
	s_waitcnt lgkmcnt(0)
	v_mfma_f32_16x16x32_bf16 v[136:139], v[176:179], v[8:11], v[136:139]
	v_mfma_f32_16x16x32_bf16 v[132:135], v[176:179], v[24:27], v[132:135]
	ds_read_b128 v[176:179], v217 offset:12288
	v_mfma_f32_16x16x32_bf16 v[144:147], v[140:143], v[4:7], 0
	v_mfma_f32_16x16x32_bf16 v[140:143], v[140:143], v[20:23], 0
	s_waitcnt lgkmcnt(0)
	v_mfma_f32_16x16x32_bf16 v[144:147], v[176:179], v[8:11], v[144:147]
	v_mfma_f32_16x16x32_bf16 v[140:143], v[176:179], v[24:27], v[140:143]
	ds_read_b128 v[176:179], v218
	s_waitcnt lgkmcnt(0)
	v_mfma_f32_16x16x32_bf16 v[120:123], v[176:179], v[12:15], v[120:123]
	v_mfma_f32_16x16x32_bf16 v[116:119], v[176:179], v[28:31], v[116:119]
	ds_read_b128 v[176:179], v218 offset:4096
	s_waitcnt lgkmcnt(0)
	v_mfma_f32_16x16x32_bf16 v[128:131], v[176:179], v[12:15], v[128:131]
	v_mfma_f32_16x16x32_bf16 v[124:127], v[176:179], v[28:31], v[124:127]
	ds_read_b128 v[176:179], v218 offset:8192
	s_waitcnt lgkmcnt(0)
	v_mfma_f32_16x16x32_bf16 v[136:139], v[176:179], v[12:15], v[136:139]
	v_mfma_f32_16x16x32_bf16 v[132:135], v[176:179], v[28:31], v[132:135]
	ds_read_b128 v[176:179], v218 offset:12288
	s_waitcnt lgkmcnt(0)
	v_mfma_f32_16x16x32_bf16 v[144:147], v[176:179], v[12:15], v[144:147]
	v_mfma_f32_16x16x32_bf16 v[140:143], v[176:179], v[28:31], v[140:143]
	ds_read_b128 v[176:179], v219
	s_waitcnt lgkmcnt(0)
	v_mfma_f32_16x16x32_bf16 v[120:123], v[176:179], v[16:19], v[120:123]
	v_mfma_f32_16x16x32_bf16 v[116:119], v[176:179], v[32:35], v[116:119]
	ds_read_b128 v[176:179], v219 offset:4096
	s_waitcnt lgkmcnt(0)
	v_mfma_f32_16x16x32_bf16 v[128:131], v[176:179], v[16:19], v[128:131]
	v_mfma_f32_16x16x32_bf16 v[124:127], v[176:179], v[32:35], v[124:127]
	ds_read_b128 v[176:179], v219 offset:8192
	s_waitcnt lgkmcnt(0)
	v_mfma_f32_16x16x32_bf16 v[136:139], v[176:179], v[16:19], v[136:139]
	v_mfma_f32_16x16x32_bf16 v[132:135], v[176:179], v[32:35], v[132:135]
	ds_read_b128 v[176:179], v219 offset:12288
	s_waitcnt lgkmcnt(0)
	v_mfma_f32_16x16x32_bf16 v[144:147], v[176:179], v[16:19], v[144:147]
	v_mfma_f32_16x16x32_bf16 v[140:143], v[176:179], v[32:35], v[140:143]
	ds_read_b128 v[176:179], v220 offset:32768
	s_waitcnt lgkmcnt(0)
	v_mfma_f32_16x16x32_bf16 v[120:123], v[176:179], v[36:39], v[120:123]
	v_mfma_f32_16x16x32_bf16 v[116:119], v[176:179], v[40:43], v[116:119]
	ds_read_b128 v[176:179], v220 offset:34816
	s_waitcnt lgkmcnt(0)
	v_mfma_f32_16x16x32_bf16 v[180:183], v[176:179], v[36:39], v[128:131]
	s_nop 2
	ds_read_b128 v[128:131], v220 offset:36864
	s_waitcnt lgkmcnt(0)
	v_mfma_f32_16x16x32_bf16 v[136:139], v[128:131], v[36:39], v[136:139]
	v_mfma_f32_16x16x32_bf16 v[132:135], v[128:131], v[40:43], v[132:135]
	ds_read_b128 v[128:131], v220 offset:38912
	v_mfma_f32_16x16x32_bf16 v[124:127], v[176:179], v[40:43], v[124:127]
	s_waitcnt lgkmcnt(0)
	v_mfma_f32_16x16x32_bf16 v[176:179], v[128:131], v[36:39], v[144:147]
	v_mfma_f32_16x16x32_bf16 v[184:187], v[128:131], v[40:43], v[140:143]
	ds_read_b128 v[128:131], v221 offset:32768
	s_waitcnt lgkmcnt(0)
	v_mfma_f32_16x16x32_bf16 v[144:147], v[128:131], v[44:47], v[120:123]
	v_mfma_f32_16x16x32_bf16 v[128:131], v[128:131], v[48:51], v[116:119]
	s_nop 2
	ds_read_b128 v[116:119], v221 offset:34816
	s_waitcnt lgkmcnt(0)
	v_mfma_f32_16x16x32_bf16 v[140:143], v[116:119], v[44:47], v[180:183]
	v_mfma_f32_16x16x32_bf16 v[124:127], v[116:119], v[48:51], v[124:127]
	ds_read_b128 v[116:119], v221 offset:36864
	s_waitcnt lgkmcnt(0)
	v_mfma_f32_16x16x32_bf16 v[136:139], v[116:119], v[44:47], v[136:139]
	v_mfma_f32_16x16x32_bf16 v[120:123], v[116:119], v[48:51], v[132:135]
	ds_read_b128 v[116:119], v221 offset:38912
	s_waitcnt lgkmcnt(0)
	v_mfma_f32_16x16x32_bf16 v[132:135], v[116:119], v[44:47], v[176:179]
	v_mfma_f32_16x16x32_bf16 v[116:119], v[116:119], v[48:51], v[184:187]
	s_cbranch_vccz .LBB0_967
	s_nop 0
	v_pk_fma_f32 v[178:179], v[144:145], s[70:71], 0 op_sel_hi:[1,0,0]
	v_pk_fma_f32 v[2:3], v[146:147], s[70:71], 0 op_sel_hi:[1,0,0]
	v_max3_f32 v176, v178, s83, v179
	v_max3_f32 v176, v176, v2, v3
	v_pk_fma_f32 v[180:181], v[140:141], s[70:71], 0 op_sel_hi:[1,0,0]
	s_mov_b64 s[0:1], 0
	v_max3_f32 v182, v176, v180, v181
	v_pk_fma_f32 v[176:177], v[142:143], s[70:71], 0 op_sel_hi:[1,0,0]
	s_nop 0
	v_max3_f32 v184, v182, v176, v177
	v_pk_fma_f32 v[182:183], v[136:137], s[70:71], 0 op_sel_hi:[1,0,0]
	s_nop 0
	v_max3_f32 v186, v184, v182, v183
	v_pk_fma_f32 v[184:185], v[138:139], s[70:71], 0 op_sel_hi:[1,0,0]
	s_nop 0
	v_max3_f32 v188, v186, v184, v185
	v_pk_fma_f32 v[186:187], v[132:133], s[70:71], 0 op_sel_hi:[1,0,0]
	s_nop 0
	v_max3_f32 v230, v188, v186, v187
	v_pk_fma_f32 v[188:189], v[134:135], s[70:71], 0 op_sel_hi:[1,0,0]
	s_nop 0
	v_max3_f32 v230, v230, v188, v189
